# v2 + attn D: waves 4-7 skip duplicate K-plane DMA (counted vmcnt per half) + GEMM store epilogue rstd via v_rsq_f32 instead of IEEE sqrt+div chain
# speedup vs baseline: 1.0118x; 1.0037x over previous
; #define AT_WAITBAR(N) asm volatile("s_waitcnt vmcnt(%0) lgkmcnt(0)\n\ts_barrier" :: "n"(N) : "memory")
; template <int DQK, int DV, bool BAND>
; DI void attn_unit(const AttnArgs& a, LAS unsigned char* lds, int tid) {
;     ...
;     if (BAND) {
;         for (int t = t_lo; t < t_hi; ++t) AT_DMA(t, (t - t_lo) * 8192);
;         AT_WAITBAR(0);
;     } else {
;         AT_DMA(t_lo, 0);
;         if (t_lo + 1 < t_hi) AT_DMA(t_lo + 1, 16384);
.LBB0_178:
	s_lshl_b32 s88, s41, 10
	s_add_i32 s72, s88, 0
	s_cmp_lt_i32 s35, 4
	s_cbranch_scc0 .Ld_skip_t0
	s_mov_b32 s41, m0
	s_mov_b32 m0, s72
	s_nop 0
	global_load_lds_dwordx4 v[4:5], off
	s_mov_b32 m0, s41
.Ld_skip_t0:
	s_lshl_b32 s41, s35, 4
	s_and_b32 s95, s41, 48
	v_or_b32_e32 v0, s95, v182
	s_ashr_i32 s41, s52, 3
	s_and_b32 s52, s41, 0xffffffe0
	v_lshlrev_b32_e32 v194, 12, v0
	s_ashr_i32 s53, s52, 31
	v_lshl_add_u64 v[0:1], s[74:75], 0, v[194:195]
	v_lshl_add_u64 v[2:3], s[52:53], 1, v[0:1]
	v_lshlrev_b32_e32 v0, 1, v156
	v_mov_b32_e32 v1, v195
	v_lshl_add_u64 v[2:3], v[2:3], 0, v[0:1]
	v_lshl_add_u64 v[2:3], v[2:3], 0, s[28:29]
	s_add_i32 s89, s92, 0xc000
	s_mov_b32 s41, m0
	s_mov_b32 m0, s89
	s_nop 0
	global_load_lds_dwordx4 v[2:3], off
	s_mov_b32 m0, s41
	s_mov_b64 s[44:45], -1
	s_and_b64 vcc, exec, s[50:51]
	v_lshl_add_u64 v[4:5], s[74:75], 0, v[158:159]
	s_cbranch_vccz .LBB0_180
	s_ashr_i32 s41, s40, 31
	v_lshl_add_u64 v[6:7], s[40:41], 1, v[4:5]
	s_mov_b64 s[44:45], 0

; #define LAS __attribute__((address_space(3)))
; #define MFMA32(a, b, c) __builtin_amdgcn_mfma_f32_32x32x16_bf16((a), (b), (c), 0, 0, 0)
; #define AT_WAITBAR(N) asm volatile("s_waitcnt vmcnt(%0) lgkmcnt(0)\n\ts_barrier" :: "n"(N) : "memory")
; template <int DQK, int DV, bool BAND>
; DI void attn_unit(const AttnArgs& a, LAS unsigned char* lds, int tid) {
;     ...
;     if (BAND) {
;         for (int t = t_lo; t < t_hi; ++t) AT_DMA(t, (t - t_lo) * 8192);
;         AT_WAITBAR(0);
;     } else {
;         AT_DMA(t_lo, 0);
;         if (t_lo + 1 < t_hi) AT_DMA(t_lo + 1, 16384);
;     }
;     int vcur = 0;
;     bf16x8 pa[4];
;     for (int t = t_lo; t < t_hi; ++t) {
;         int vnext = 0;
;         if (BAND) { vcur = (t - t_lo) * 8192; }
;         else {
;             if (t + 1 < t_hi) AT_WAITBAR(NLD); else AT_WAITBAR(0);
;             vnext = vcur == 32768 ? 0 : vcur + 16384; const int vnn = vnext == 32768 ? 0 : vnext + 16384;
;             if (t + 2 < t_hi) AT_DMA(t + 2, vnn);
;         }
;         bool active = true;
;         if (BAND) active = (64 * t + 63 >= qw - 64) && (64 * t <= qw + 95);
;         if (active) {
;             f32x16 p0, p1;
;             const LAS unsigned char* kb = lds + KBUF + vcur + hi * 1024 + r32 * 16;
; #pragma unroll
;             for (int dg = 0; dg < ND0; dg += KG) {
;                 bf16x8 kf0[KG], kf1[KG];
; #pragma unroll
;                 for (int j = 0; j < KG; ++j) if (dg + j < ND0) { kf0[j] = *(const LAS bf16x8*)(kb + (dg + j) * 2048); kf1[j] = *(const LAS bf16x8*)(kb + (dg + j) * 2048 + 512); }
;                 __builtin_amdgcn_sched_barrier(0);
; #pragma unroll
;                 for (int j = 0; j < KG; ++j) if (dg + j < ND0) {
;                     if (dg + j == 0) { p0 = MFMA32(kf0[j], qf[0], negm); p1 = MFMA32(kf1[j], qf[0], negm); }
;                     else { p0 = MFMA32(kf0[j], qf[dg + j], p0); p1 = MFMA32(kf1[j], qf[dg + j], p1); }
;                 }
;             }
;             s16x4 vlo[8], vhi[8];
;             if (VPRE) { const LAS unsigned char* vp_ = lds + VBUF + vcur + ((lane >> 4) & 1) * 32 + (lane & 3) * 8 + (4 * hi + ((lane & 15) >> 2)) * 64;
; #pragma unroll
;               for (int d = 0; d < 2; ++d)
; #pragma unroll
;                   for (int ks = 0; ks < 4; ++ks) { vlo[d * 4 + ks] = vtr(vp_ + d * 4096 + ks * 1024); vhi[d * 4 + ks] = vtr(vp_ + d * 4096 + ks * 1024 + 512); } }
.LBB0_186:
	s_lshl_b32 s24, s35, 8
	v_lshl_add_u64 v[2:3], s[74:75], 0, v[194:195]
	s_lshl_b64 s[70:71], s[52:53], 1
	s_add_i32 s24, s24, 0
	v_lshl_add_u64 v[2:3], v[2:3], 0, s[70:71]
	v_mov_b32_e32 v1, v195
	s_add_i32 s81, s24, 0x18000
	s_addk_i32 s72, 0x4000
	s_cmp_lt_i32 s35, 4
	s_cbranch_scc0 .Ld_skip_t1
	s_mov_b32 s24, m0
	s_mov_b32 m0, s72
	s_nop 0
	global_load_lds_dwordx4 v[4:5], off
	s_mov_b32 m0, s24
.Ld_skip_t1:
	v_lshl_add_u64 v[2:3], v[2:3], 0, v[0:1]
	s_mov_b64 s[52:53], 0x40080
	v_lshl_add_u64 v[2:3], v[2:3], 0, s[52:53]
	s_add_i32 s24, s92, 0x10000
	s_mov_b32 s41, m0
	s_mov_b32 m0, s24
	s_nop 0
	global_load_lds_dwordx4 v[2:3], off
	s_mov_b32 m0, s41
	s_ashr_i32 s41, s40, 31
	s_mov_b32 s24, s40
	s_lshl_b64 s[40:41], s[40:41], 1
	s_add_u32 s52, s74, s40
	s_addc_u32 s53, s75, s41
	s_lshl_b64 s[72:73], s[24:25], 1
	s_add_u32 s90, s76, s72
	s_addc_u32 s91, s77, s73
	s_lshl_b64 s[40:41], s[54:55], 1
	s_add_u32 s54, s74, s40
	s_addc_u32 s55, s75, s41
	s_lshl_b64 s[40:41], s[78:79], 1
	s_add_u32 s76, s76, s40
	s_addc_u32 s77, s77, s41
	s_add_u32 s74, s74, s70
	s_addc_u32 s75, s75, s71
	v_lshl_add_u64 v[0:1], s[74:75], 0, v[0:1]
	s_movk_i32 s74, 0xff80
	v_lshl_add_u64 v[2:3], s[90:91], 0, v[164:165]
	s_mov_b32 s75, -1
	v_lshl_add_u64 v[2:3], v[2:3], 0, s[74:75]
	v_lshl_add_u64 v[4:5], s[52:53], 0, v[162:163]
	s_cmp_lt_i32 s35, 4
	s_cbranch_scc0 .Ld_w0_hi
	s_waitcnt vmcnt(3) lgkmcnt(0)
	s_branch .Ld_w0_bar
.Ld_w0_hi:
	s_waitcnt vmcnt(2) lgkmcnt(0)
.Ld_w0_bar:
	s_barrier
	v_cndmask_b32_e64 v3, v5, v3, s[46:47]
	v_cndmask_b32_e64 v2, v4, v2, s[46:47]
	s_add_i32 s24, 0, 0x8000
	s_add_i32 s46, s83, s24
	s_mov_b32 s47, m0
	s_mov_b32 m0, s46
	s_nop 0
	global_load_lds_dwordx4 v[2:3], off
	s_mov_b32 m0, s47
	v_lshl_add_u64 v[2:3], s[76:77], 0, v[164:165]
	v_lshl_add_u64 v[2:3], v[2:3], 0, s[74:75]
	v_lshl_add_u64 v[4:5], s[54:55], 0, v[162:163]
	v_cndmask_b32_e64 v3, v5, v3, s[48:49]
	v_cndmask_b32_e64 v2, v4, v2, s[48:49]
	s_add_i32 s24, s88, s24
	s_cmp_lt_i32 s35, 4
	s_cbranch_scc0 .Ld_skip_t2
	s_mov_b32 s46, m0
	s_mov_b32 m0, s24
	s_nop 0
	global_load_lds_dwordx4 v[2:3], off
	s_mov_b32 m0, s46
.Ld_skip_t2:
	v_lshl_add_u64 v[0:1], v[0:1], 0, v[194:195]
	s_mov_b64 s[46:47], 0x80080
	v_lshl_add_u64 v[0:1], v[0:1], 0, s[46:47]
	s_add_i32 s92, s92, 0x14000
	s_mov_b32 s24, m0
	s_mov_b32 m0, s92
	s_nop 0
	global_load_lds_dwordx4 v[0:1], off
	s_mov_b32 m0, s24
	ds_read_b128 v[0:3], v183
	ds_read_b128 v[20:23], v183 offset:512
	ds_read_b128 v[24:27], v183 offset:2048
	ds_read_b128 v[28:31], v183 offset:2560
	ds_read_b128 v[32:35], v183 offset:4096
	ds_read_b128 v[36:39], v183 offset:4608
	ds_read_b128 v[40:43], v183 offset:6144
	ds_read_b128 v[44:47], v183 offset:6656
	s_movk_i32 s49, 0x4000
	s_mov_b32 s46, 1
	v_lshl_add_u32 v171, v157, 2, s81
	v_lshl_add_u32 v173, v184, 2, s81
	s_waitcnt lgkmcnt(7)
	v_mfma_f32_32x32x16_bf16 v[4:19], v[0:3], v[96:99], 0
	s_waitcnt lgkmcnt(6)
	v_mfma_f32_32x32x16_bf16 v[48:63], v[20:23], v[96:99], 0
	s_waitcnt lgkmcnt(5)
	v_mfma_f32_32x32x16_bf16 v[4:19], v[24:27], v[100:103], v[4:19]
	s_waitcnt lgkmcnt(4)
	v_mfma_f32_32x32x16_bf16 v[48:63], v[28:31], v[100:103], v[48:63]
	ds_read_b128 v[0:3], v183 offset:8192
	ds_read_b128 v[20:23], v183 offset:8704
	ds_read_b128 v[24:27], v183 offset:10240
	ds_read_b128 v[28:31], v183 offset:10752
	s_waitcnt lgkmcnt(7)
	v_mfma_f32_32x32x16_bf16 v[4:19], v[32:35], v[104:107], v[4:19]
	s_waitcnt lgkmcnt(6)
	v_mfma_f32_32x32x16_bf16 v[48:63], v[36:39], v[104:107], v[48:63]
	s_waitcnt lgkmcnt(5)
	v_mfma_f32_32x32x16_bf16 v[4:19], v[40:43], v[108:111], v[4:19]
	s_waitcnt lgkmcnt(4)
	v_mfma_f32_32x32x16_bf16 v[48:63], v[44:47], v[108:111], v[48:63]
	s_waitcnt lgkmcnt(3)
	v_mfma_f32_32x32x16_bf16 v[4:19], v[0:3], v[112:115], v[4:19]
	s_waitcnt lgkmcnt(2)
	v_mfma_f32_32x32x16_bf16 v[48:63], v[20:23], v[112:115], v[48:63]
	ds_read_b64_tr_b16 v[0:1], v185 offset:49152
	ds_read_b64_tr_b16 v[2:3], v185 offset:49664
	ds_read_b64_tr_b16 v[64:65], v185 offset:50176
	ds_read_b64_tr_b16 v[66:67], v185 offset:50688
	ds_read_b64_tr_b16 v[68:69], v185 offset:51200
	ds_read_b64_tr_b16 v[70:71], v185 offset:51712
	ds_read_b64_tr_b16 v[72:73], v185 offset:52224
	ds_read_b64_tr_b16 v[74:75], v185 offset:52736
	ds_read_b64_tr_b16 v[20:21], v185 offset:53248
	ds_read_b64_tr_b16 v[22:23], v185 offset:53760
	ds_read_b64_tr_b16 v[76:77], v185 offset:54272
	ds_read_b64_tr_b16 v[78:79], v185 offset:54784
	ds_read_b64_tr_b16 v[80:81], v185 offset:55296
	ds_read_b64_tr_b16 v[82:83], v185 offset:55808
	ds_read_b64_tr_b16 v[84:85], v185 offset:56320
	ds_read_b64_tr_b16 v[86:87], v185 offset:56832
	s_waitcnt lgkmcnt(14)
; #define LAS __attribute__((address_space(3)))
; template <int DQK, int DV, bool BAND>
; DI void attn_unit(const AttnArgs& a, LAS unsigned char* lds, int tid) {
;     ...
;             if (!a.nomax) {
;             float mx = fmaxf(p0[0], p1[0]);
; #pragma unroll
;             for (int r = 1; r < 16; ++r) mx = fmaxf(fmaxf(mx, p0[r]), p1[r]);
;             { const unsigned mu = __float_as_uint(mx); auto rr = __builtin_amdgcn_permlane32_swap(mu, mu, false, false); mx = fmaxf(__uint_as_float(rr[0]), __uint_as_float(rr[1])); }
;             if (first || __any(mx > 8.0f)) {
;                 const float delta = first ? fmaxf(mx, -1e4f) : fmaxf(mx, 0.f);
;                 m_run += delta;
; #pragma unroll
;                 for (int r = 0; r < 16; ++r) { p0[r] -= delta; p1[r] -= delta; negm[r] = -m_run; }
;                 if (!first) {
;                     const float alpha = __builtin_amdgcn_exp2f(-delta);
;                     if (hi == 0) scr[r32] = alpha;
; #pragma unroll
;                     for (int g = 0; g < 4; ++g) { const f32x4 al = *(const LAS f32x4*)(scr + 8 * g + 4 * hi);
;                         lacc[4 * g] *= al.x; lacc[4 * g + 1] *= al.y; lacc[4 * g + 2] *= al.z; lacc[4 * g + 3] *= al.w;
; #pragma unroll
;                         for (int d = 0; d < NDB; ++d) { o[d][4 * g] *= al.x; o[d][4 * g + 1] *= al.y; o[d][4 * g + 2] *= al.z; o[d][4 * g + 3] *= al.w; } }
;                 }
;                 first = false;
;             }
;             }
; #pragma unroll
;             for (int r = 0; r < 16; ++r) { p0[r] = __builtin_amdgcn_exp2f(p0[r]); p1[r] = __builtin_amdgcn_exp2f(p1[r]); }
;             { u32x4 w;
;               w.x = pk2(p0[0], p0[1]); w.y = pk2(p0[2], p0[3]); w.z = pk2(p0[4], p0[5]); w.w = pk2(p0[6], p0[7]); pa[0] = __builtin_bit_cast(bf16x8, w);
;               w.x = pk2(p0[8], p0[9]); w.y = pk2(p0[10], p0[11]); w.z = pk2(p0[12], p0[13]); w.w = pk2(p0[14], p0[15]); pa[1] = __builtin_bit_cast(bf16x8, w);
;               w.x = pk2(p1[0], p1[1]); w.y = pk2(p1[2], p1[3]); w.z = pk2(p1[4], p1[5]); w.w = pk2(p1[6], p1[7]); pa[2] = __builtin_bit_cast(bf16x8, w);
;               w.x = pk2(p1[8], p1[9]); w.y = pk2(p1[10], p1[11]); w.z = pk2(p1[12], p1[13]); w.w = pk2(p1[14], p1[15]); pa[3] = __builtin_bit_cast(bf16x8, w); }
;             if (DQK > 96) { AT_PV(vcur); } else {
	v_mfma_f32_32x32x16_bf16 v[4:19], v[24:27], v[116:119], v[4:19]
	v_mfma_f32_32x32x16_bf16 v[48:63], v[28:31], v[116:119], v[48:63]
	s_nop 11
	v_max_f32_e32 v24, v48, v48
	v_max_f32_e32 v25, v4, v4
	v_max_f32_e32 v24, v25, v24
	v_max3_f32 v24, v24, v5, v49
	v_max3_f32 v24, v24, v6, v50
	v_max3_f32 v24, v24, v7, v51
	v_max3_f32 v24, v24, v8, v52
	v_max3_f32 v24, v24, v9, v53
	v_max3_f32 v24, v24, v10, v54
	v_max3_f32 v24, v24, v11, v55
	v_max3_f32 v24, v24, v12, v56
	v_max3_f32 v24, v24, v13, v57
	v_max3_f32 v24, v24, v14, v58
	v_max3_f32 v24, v24, v15, v59
	v_max3_f32 v24, v24, v16, v60
	v_max3_f32 v24, v24, v17, v61
	v_max3_f32 v24, v24, v18, v62
	v_max3_f32 v24, v24, v19, v63
	v_mov_b32_e32 v25, v24
	s_nop 1
	v_permlane32_swap_b32_e32 v24, v25
	s_mov_b32 s24, 0xc61c4000
	v_max3_f32 v120, v24, v25, s24
	v_sub_f32_e32 v4, v4, v120
	v_sub_f32_e32 v5, v5, v120
	v_sub_f32_e32 v6, v6, v120
	v_sub_f32_e32 v7, v7, v120
	v_sub_f32_e32 v8, v8, v120
	v_sub_f32_e32 v9, v9, v120
	v_sub_f32_e32 v10, v10, v120
	v_sub_f32_e32 v11, v11, v120
	v_exp_f32_e32 v4, v4
	v_exp_f32_e32 v5, v5
	v_exp_f32_e32 v6, v6
	v_exp_f32_e32 v7, v7
	v_exp_f32_e32 v8, v8
	v_exp_f32_e32 v9, v9
	v_exp_f32_e32 v10, v10
	v_exp_f32_e32 v11, v11
	v_cvt_pk_bf16_f32 v32, v4, v5
	v_cvt_pk_bf16_f32 v33, v6, v7
	v_cvt_pk_bf16_f32 v34, v8, v9
	v_cvt_pk_bf16_f32 v35, v10, v11
	v_sub_f32_e32 v24, v12, v120
	v_sub_f32_e32 v25, v13, v120
	v_exp_f32_e32 v41, v24
	v_exp_f32_e32 v42, v25
	v_sub_f32_e32 v26, v14, v120
	v_sub_f32_e32 v36, v15, v120
	v_sub_f32_e32 v37, v16, v120
	v_sub_f32_e32 v38, v17, v120
	v_sub_f32_e32 v39, v18, v120
	v_sub_f32_e32 v40, v19, v120
	v_mov_b64_e32 v[94:95], s[62:63]
	v_exp_f32_e32 v89, v26
	v_exp_f32_e32 v90, v36
	v_exp_f32_e32 v91, v37
	v_exp_f32_e32 v121, v38
	v_exp_f32_e32 v122, v39
	v_exp_f32_e32 v123, v40
	v_mov_b64_e32 v[92:93], s[60:61]
	v_mfma_f32_32x32x16_bf16 v[0:15], v[32:35], v[0:3], 0
	v_cvt_pk_bf16_f32 v88, v41, v42
	v_cvt_pk_bf16_f32 v89, v89, v90
	v_cvt_pk_bf16_f32 v90, v91, v121
	v_cvt_pk_bf16_f32 v91, v122, v123
	v_sub_f32_e32 v48, v48, v120
	v_sub_f32_e32 v49, v49, v120
	v_sub_f32_e32 v50, v50, v120
	s_waitcnt lgkmcnt(6)
	v_mfma_f32_32x32x16_bf16 v[16:31], v[32:35], v[20:23], 0
	v_sub_f32_e32 v51, v51, v120
	v_sub_f32_e32 v52, v52, v120
	v_sub_f32_e32 v53, v53, v120
	v_sub_f32_e32 v54, v54, v120
	v_sub_f32_e32 v55, v55, v120
	v_exp_f32_e32 v48, v48
	v_exp_f32_e32 v49, v49
	v_mfma_f32_32x32x16_bf16 v[32:47], v[32:35], v[92:95], 0
	v_exp_f32_e32 v50, v50
	v_exp_f32_e32 v51, v51
	v_exp_f32_e32 v52, v52
	v_exp_f32_e32 v53, v53
	v_exp_f32_e32 v54, v54
	v_exp_f32_e32 v55, v55
	v_cvt_pk_bf16_f32 v48, v48, v49
	v_mfma_f32_32x32x16_bf16 v[0:15], v[88:91], v[64:67], v[0:15]
	v_cvt_pk_bf16_f32 v49, v50, v51
	v_cvt_pk_bf16_f32 v50, v52, v53
	v_cvt_pk_bf16_f32 v51, v54, v55
	v_sub_f32_e32 v52, v56, v120
	v_sub_f32_e32 v53, v57, v120
	v_sub_f32_e32 v54, v58, v120
	v_sub_f32_e32 v55, v59, v120
	s_waitcnt lgkmcnt(4)
	v_mfma_f32_32x32x16_bf16 v[16:31], v[88:91], v[76:79], v[16:31]
	v_sub_f32_e32 v56, v60, v120
	v_sub_f32_e32 v57, v61, v120
	v_sub_f32_e32 v58, v62, v120
	v_sub_f32_e32 v59, v63, v120
	v_exp_f32_e32 v52, v52
	v_exp_f32_e32 v53, v53
	v_exp_f32_e32 v54, v54
	v_mfma_f32_32x32x16_bf16 v[32:47], v[88:91], v[92:95], v[32:47]
	v_exp_f32_e32 v55, v55
	v_exp_f32_e32 v56, v56
	v_exp_f32_e32 v57, v57
	v_exp_f32_e32 v58, v58
	v_exp_f32_e32 v59, v59
	v_cvt_pk_bf16_f32 v52, v52, v53
	v_cvt_pk_bf16_f32 v53, v54, v55
	v_mfma_f32_32x32x16_bf16 v[0:15], v[48:51], v[68:71], v[0:15]
	v_cvt_pk_bf16_f32 v54, v56, v57
	v_cvt_pk_bf16_f32 v55, v58, v59
	s_add_u32 s24, s70, s66
	s_addc_u32 s47, s71, s67
	s_add_u32 s56, s24, s56
	s_addc_u32 s57, s47, s57
	s_add_u32 s40, s64, s40
	s_waitcnt lgkmcnt(2)
	v_mfma_f32_32x32x16_bf16 v[16:31], v[48:51], v[80:83], v[16:31]
	s_addc_u32 s41, s65, s41
	v_add_f32_e32 v200, 0, v120
	v_add_lshl_u32 v194, v182, s95, 12
	v_lshl_add_u64 v[178:179], v[168:169], 0, s[40:41]
	s_add_u32 s40, s64, s72
	s_addc_u32 s41, s65, s73
	v_readlane_b32 s72, v255, 4
	v_mfma_f32_32x32x16_bf16 v[32:47], v[48:51], v[92:95], v[32:47]
	v_xor_b32_e32 v48, 0x80000000, v200
	v_lshl_add_u64 v[50:51], s[56:57], 0, v[194:195]
	v_lshl_add_u64 v[174:175], v[166:167], 0, v[50:51]
	v_lshl_add_u64 v[180:181], v[168:169], 0, s[40:41]
	s_mov_b32 s47, 3
	v_mov_b32_e32 v49, v48
	v_mov_b32_e32 v50, v48
	v_mfma_f32_32x32x16_bf16 v[0:15], v[52:55], v[72:75], v[0:15]
	v_mov_b32_e32 v51, v48
	v_mov_b32_e32 v56, v48
	v_mov_b32_e32 v57, v48
	v_mov_b32_e32 v58, v48
	v_mov_b32_e32 v59, v48
	v_mov_b32_e32 v60, v48
	v_mov_b32_e32 v61, v48
	s_waitcnt lgkmcnt(0)
	v_mfma_f32_32x32x16_bf16 v[16:31], v[52:55], v[84:87], v[16:31]
	v_mov_b32_e32 v62, v48
	v_mov_b32_e32 v63, v48
	v_readlane_b32 s64, v253, 57
	v_readlane_b32 s67, v253, 59
	v_readlane_b32 s66, v253, 60
	s_movk_i32 s95, 0xc00
	s_mov_b32 s90, 0x41000000
	v_mfma_f32_32x32x16_bf16 v[32:47], v[52:55], v[92:95], v[32:47]
	v_mov_b32_e32 v52, v48
	v_mov_b32_e32 v53, v48
	v_mov_b32_e32 v54, v48
	v_mov_b32_e32 v55, v48
	s_mov_b64 s[70:71], 0x1000
	s_mov_b64 s[74:75], 0x60000
	s_mov_b64 s[76:77], 0x30000
	v_readlane_b32 s91, v254, 40
	v_readlane_b32 s73, v255, 5
	v_readlane_b32 s65, v253, 58
	s_add_i32 s24, s47, -1
	s_cmp_ge_u32 s24, s69
	s_mov_b64 s[40:41], -1
	s_cbranch_scc0 .LBB0_188

; #define AT_WAITBAR(N) asm volatile("s_waitcnt vmcnt(%0) lgkmcnt(0)\n\ts_barrier" :: "n"(N) : "memory")
; template <int DQK, int DV, bool BAND>
; DI void attn_unit(const AttnArgs& a, LAS unsigned char* lds, int tid) {
;     ...
;             if (t + 1 < t_hi) AT_WAITBAR(NLD); else AT_WAITBAR(0);
.LBB0_188:
	s_andn2_b64 vcc, exec, s[40:41]
	s_cbranch_vccnz .LBB0_190
	s_cmp_lt_i32 s35, 4
	s_cbranch_scc0 .Ld_w1_hi
	s_waitcnt vmcnt(3) lgkmcnt(0)
	s_branch .Ld_w1_bar

; #define AT_WAITBAR(N) asm volatile("s_waitcnt vmcnt(%0) lgkmcnt(0)\n\ts_barrier" :: "n"(N) : "memory")
; template <int DQK, int DV, bool BAND>
; DI void attn_unit(const AttnArgs& a, LAS unsigned char* lds, int tid) {
;     ...
;             if (t + 1 < t_hi) AT_WAITBAR(NLD); else AT_WAITBAR(0);
.Ld_w1_bar:
	s_barrier

; template <int DQK, int DV, bool BAND>
; DI void attn_unit(const AttnArgs& a, LAS unsigned char* lds, int tid) {
;     ...
;             if (t + 2 < t_hi) AT_DMA(t + 2, vnn);
.LBB0_195:
	s_add_i32 s40, s40, s88
	s_cmp_lt_i32 s35, 4
	s_cbranch_scc0 .Ld_skip_lp
	s_mov_b32 s41, m0
	s_mov_b32 m0, s40
	s_nop 0
	global_load_lds_dwordx4 v[66:67], off
	s_mov_b32 m0, s41
.Ld_skip_lp:
	s_add_i32 s24, s89, s24
	s_mov_b32 s40, m0
	s_mov_b32 m0, s24
	s_nop 0
	global_load_lds_dwordx4 v[174:175], off
	s_mov_b32 m0, s40

; #define PG8_GAS __attribute__((address_space(1)))
;     __device__ __forceinline__ void operator()(const f32x4 (&acc)[2][2][4][2], const Unit& u, int wr, int wc, int fr, int fq) const {
;     ...
;         if (ss) { unsigned long long sv[2][4];
; #pragma unroll
;             for (int ai = 0; ai < 2; ++ai)
; #pragma unroll
;                 for (int m = 0; m < 4; ++m) sv[ai][m] = ((const PG8_GAS unsigned long long*)ss)[row0 + ai * HALF + m * 16];
; #pragma unroll
;             for (int ai = 0; ai < 2; ++ai)
; #pragma unroll
;                 for (int m = 0; m < 4; ++m) rsv[ai][m] = 1.0f / sqrtf((float)sv[ai][m] * (1.0f / (1024.0f * 1048576.0f)) + 1e-6f);
.LBB0_429:
	v_lshl_add_u32 v138, s77, 8, v141
	s_andn2_b64 vcc, exec, s[74:75]
	v_ashrrev_i32_e32 v139, 31, v138
	s_cbranch_vccnz .LBB0_431
	v_lshl_add_u64 v[144:145], v[138:139], 3, s[54:55]
	global_load_dwordx2 v[156:157], v[144:145], off
	global_load_dwordx2 v[160:161], v[144:145], off offset:128
	global_load_dwordx2 v[146:147], v[144:145], off offset:256
	global_load_dwordx2 v[154:155], v[144:145], off offset:384
	global_load_dwordx2 v[152:153], v[144:145], off offset:1024
	global_load_dwordx2 v[150:151], v[144:145], off offset:1152
	global_load_dwordx2 v[148:149], v[144:145], off offset:1280
	s_nop 0
	global_load_dwordx2 v[144:145], v[144:145], off offset:1408
	s_waitcnt vmcnt(0)
	v_ffbh_u32_e32 v140, v157
	v_min_u32_e32 v140, 32, v140
	v_lshlrev_b64 v[156:157], v140, v[156:157]
	v_min_u32_e32 v142, 1, v156
	v_or_b32_e32 v142, v157, v142
	v_cvt_f32_u32_e32 v142, v142
	v_sub_u32_e32 v140, 32, v140
	v_ldexp_f32 v140, v142, v140
	v_fmamk_f32 v140, v140, 0x30800000, v237
	v_rsq_f32_e32 v140, v140
	s_nop 0
	v_ffbh_u32_e32 v142, v161
	v_min_u32_e32 v142, 32, v142
	v_lshlrev_b64 v[156:157], v142, v[160:161]
	v_min_u32_e32 v156, 1, v156
	v_or_b32_e32 v156, v157, v156
	v_cvt_f32_u32_e32 v156, v156
	v_sub_u32_e32 v142, 32, v142
	v_ldexp_f32 v142, v156, v142
	v_fmamk_f32 v142, v142, 0x30800000, v237
	v_rsq_f32_e32 v142, v142
	s_nop 0
	v_ffbh_u32_e32 v156, v147
	v_min_u32_e32 v156, 32, v156
	v_lshlrev_b64 v[146:147], v156, v[146:147]
	v_min_u32_e32 v146, 1, v146
	v_or_b32_e32 v146, v147, v146
	v_cvt_f32_u32_e32 v146, v146
	v_sub_u32_e32 v147, 32, v156
	v_ldexp_f32 v146, v146, v147
	v_fmamk_f32 v146, v146, 0x30800000, v237
	v_rsq_f32_e32 v146, v146
	s_nop 0
	v_ffbh_u32_e32 v147, v155
	v_min_u32_e32 v147, 32, v147
	v_lshlrev_b64 v[154:155], v147, v[154:155]
	v_min_u32_e32 v154, 1, v154
	v_or_b32_e32 v154, v155, v154
	v_cvt_f32_u32_e32 v154, v154
	v_sub_u32_e32 v147, 32, v147
	v_ldexp_f32 v147, v154, v147
	v_fmamk_f32 v147, v147, 0x30800000, v237
	v_rsq_f32_e32 v154, v147
	s_nop 0
	v_ffbh_u32_e32 v147, v153
	v_min_u32_e32 v147, 32, v147
	v_lshlrev_b64 v[152:153], v147, v[152:153]
	v_min_u32_e32 v152, 1, v152
	v_or_b32_e32 v152, v153, v152
	v_cvt_f32_u32_e32 v152, v152
	v_sub_u32_e32 v147, 32, v147
	v_ldexp_f32 v147, v152, v147
	v_fmamk_f32 v147, v147, 0x30800000, v237
	v_rsq_f32_e32 v152, v147
	s_nop 0
	v_ffbh_u32_e32 v147, v151
	v_min_u32_e32 v147, 32, v147
	v_lshlrev_b64 v[150:151], v147, v[150:151]
	v_min_u32_e32 v150, 1, v150
	v_or_b32_e32 v150, v151, v150
	v_cvt_f32_u32_e32 v150, v150
	v_sub_u32_e32 v147, 32, v147
	v_ldexp_f32 v147, v150, v147
	v_fmamk_f32 v147, v147, 0x30800000, v237
	v_rsq_f32_e32 v150, v147
	s_nop 0
	v_ffbh_u32_e32 v147, v149
	v_min_u32_e32 v147, 32, v147
	v_lshlrev_b64 v[148:149], v147, v[148:149]
	v_min_u32_e32 v148, 1, v148
	v_or_b32_e32 v148, v149, v148
	v_cvt_f32_u32_e32 v148, v148
	v_sub_u32_e32 v147, 32, v147
	v_ldexp_f32 v147, v148, v147
	v_fmamk_f32 v147, v147, 0x30800000, v237
	v_rsq_f32_e32 v148, v147
	s_nop 0
	v_ffbh_u32_e32 v147, v145
	v_min_u32_e32 v147, 32, v147
	v_lshlrev_b64 v[144:145], v147, v[144:145]
	v_min_u32_e32 v144, 1, v144
	v_or_b32_e32 v144, v145, v144
	v_cvt_f32_u32_e32 v144, v144
	v_sub_u32_e32 v145, 32, v147
	v_ldexp_f32 v144, v144, v145
	v_fmamk_f32 v144, v144, 0x30800000, v237
	v_rsq_f32_e32 v144, v144
	s_nop 0
	s_branch .LBB0_432

; #define PG8_GAS __attribute__((address_space(1)))
;     __device__ __forceinline__ void operator()(const f32x4 (&acc)[2][2][4][2], const Unit& u, int wr, int wc, int fr, int fq) const {
;     ...
;         if (ss) { unsigned long long sv[2][4];
; #pragma unroll
;             for (int ai = 0; ai < 2; ++ai)
; #pragma unroll
;                 for (int m = 0; m < 4; ++m) sv[ai][m] = ((const PG8_GAS unsigned long long*)ss)[row0 + ai * HALF + m * 16];
; #pragma unroll
;             for (int ai = 0; ai < 2; ++ai)
; #pragma unroll
;                 for (int m = 0; m < 4; ++m) rsv[ai][m] = 1.0f / sqrtf((float)sv[ai][m] * (1.0f / (1024.0f * 1048576.0f)) + 1e-6f);
.LBB0_463:
	v_lshl_add_u32 v142, s35, 8, v164
	s_andn2_b64 vcc, exec, s[20:21]
	v_ashrrev_i32_e32 v143, 31, v142
	s_cbranch_vccnz .LBB0_465
	v_lshl_add_u64 v[144:145], v[142:143], 3, s[54:55]
	global_load_dwordx2 v[156:157], v[144:145], off
	global_load_dwordx2 v[160:161], v[144:145], off offset:128
	global_load_dwordx2 v[154:155], v[144:145], off offset:256
	global_load_dwordx2 v[152:153], v[144:145], off offset:384
	global_load_dwordx2 v[150:151], v[144:145], off offset:1024
	global_load_dwordx2 v[148:149], v[144:145], off offset:1152
	global_load_dwordx2 v[146:147], v[144:145], off offset:1280
	s_nop 0
	global_load_dwordx2 v[144:145], v[144:145], off offset:1408
	s_waitcnt vmcnt(0)
	v_ffbh_u32_e32 v158, v157
	v_min_u32_e32 v158, 32, v158
	v_lshlrev_b64 v[156:157], v158, v[156:157]
	v_min_u32_e32 v156, 1, v156
	v_or_b32_e32 v156, v157, v156
	v_cvt_f32_u32_e32 v156, v156
	v_sub_u32_e32 v157, 32, v158
	v_ldexp_f32 v156, v156, v157
	v_fmamk_f32 v156, v156, 0x30800000, v237
	v_rsq_f32_e32 v158, v156
	s_nop 0
	v_ffbh_u32_e32 v156, v161
	v_min_u32_e32 v159, 32, v156
	v_lshlrev_b64 v[156:157], v159, v[160:161]
	v_min_u32_e32 v156, 1, v156
	v_or_b32_e32 v156, v157, v156
	v_cvt_f32_u32_e32 v156, v156
	v_sub_u32_e32 v157, 32, v159
	v_ldexp_f32 v156, v156, v157
	v_fmamk_f32 v156, v156, 0x30800000, v237
	v_rsq_f32_e32 v156, v156
	s_nop 0
	v_ffbh_u32_e32 v157, v155
	v_min_u32_e32 v157, 32, v157
	v_lshlrev_b64 v[154:155], v157, v[154:155]
	v_min_u32_e32 v154, 1, v154
	v_or_b32_e32 v154, v155, v154
	v_cvt_f32_u32_e32 v154, v154
	v_sub_u32_e32 v155, 32, v157
	v_ldexp_f32 v154, v154, v155
	v_fmamk_f32 v154, v154, 0x30800000, v237
	v_rsq_f32_e32 v154, v154
	s_nop 0
	v_ffbh_u32_e32 v155, v153
	v_min_u32_e32 v155, 32, v155
	v_lshlrev_b64 v[152:153], v155, v[152:153]
	v_min_u32_e32 v152, 1, v152
	v_or_b32_e32 v152, v153, v152
	v_cvt_f32_u32_e32 v152, v152
	v_sub_u32_e32 v153, 32, v155
	v_ldexp_f32 v152, v152, v153
	v_fmamk_f32 v152, v152, 0x30800000, v237
	v_rsq_f32_e32 v152, v152
	s_nop 0
	v_ffbh_u32_e32 v153, v151
	v_min_u32_e32 v153, 32, v153
	v_lshlrev_b64 v[150:151], v153, v[150:151]
	v_min_u32_e32 v150, 1, v150
	v_or_b32_e32 v150, v151, v150
	v_cvt_f32_u32_e32 v150, v150
	v_sub_u32_e32 v151, 32, v153
	v_ldexp_f32 v150, v150, v151
	v_fmamk_f32 v150, v150, 0x30800000, v237
	v_rsq_f32_e32 v150, v150
	s_nop 0
	v_ffbh_u32_e32 v151, v149
	v_min_u32_e32 v151, 32, v151
	v_lshlrev_b64 v[148:149], v151, v[148:149]
	v_min_u32_e32 v148, 1, v148
	v_or_b32_e32 v148, v149, v148
	v_cvt_f32_u32_e32 v148, v148
	v_sub_u32_e32 v149, 32, v151
	v_ldexp_f32 v148, v148, v149
	v_fmamk_f32 v148, v148, 0x30800000, v237
	v_rsq_f32_e32 v148, v148
	s_nop 0
	v_ffbh_u32_e32 v149, v147
	v_min_u32_e32 v149, 32, v149
	v_lshlrev_b64 v[146:147], v149, v[146:147]
	v_min_u32_e32 v146, 1, v146
	v_or_b32_e32 v146, v147, v146
	v_cvt_f32_u32_e32 v146, v146
	v_sub_u32_e32 v147, 32, v149
	v_ldexp_f32 v146, v146, v147
	v_fmamk_f32 v146, v146, 0x30800000, v237
	v_rsq_f32_e32 v146, v146
	s_nop 0
	v_ffbh_u32_e32 v147, v145
	v_min_u32_e32 v147, 32, v147
	v_lshlrev_b64 v[144:145], v147, v[144:145]
	v_min_u32_e32 v144, 1, v144
	v_or_b32_e32 v144, v145, v144
	v_cvt_f32_u32_e32 v144, v144
	v_sub_u32_e32 v145, 32, v147
	v_ldexp_f32 v144, v144, v145
	v_fmamk_f32 v144, v144, 0x30800000, v237
	v_rsq_f32_e32 v144, v144
	s_nop 0
	s_branch .LBB0_466
